# adaLN loads batched + LN_attn L0 loop: params hoisted, next-row prefetch
# speedup vs baseline: 1.0141x; 1.0048x over previous
; DI void st4(bf16_t* p, float a, float b, float c, float d) { u32x2 w = {pk2(a, b), pk2(c, d)}; *(u32x2*)p = w; }
; DI void phase_ln(const Params& p, const float* g, const float* bta, const float* sh, const float* sc, bool writex, int bid, int nb) {
;     ...
;   for (int row = bid * 8 + wid; row < NTOK; row += nb * 8) {
;     float* xr = p.out + (size_t)row * DM; const int b = row >> 12;
;     f32x4 v[4]; float s = 0.f;
; #pragma unroll
;     for (int e = 0; e < 4; ++e) { v[e] = *(const f32x4*)(xr + e * 256 + lane * 4); s += (v[e][0] + v[e][1]) + (v[e][2] + v[e][3]); }
; #pragma unroll
;     for (int o = 32; o > 0; o >>= 1) s += __shfl_xor(s, o);
;     const float mu = s * (1.f / 1024.f); float q = 0.f;
; #pragma unroll
;     for (int e = 0; e < 4; ++e) { v[e] -= mu; q += (v[e][0] * v[e][0] + v[e][1] * v[e][1]) + (v[e][2] * v[e][2] + v[e][3] * v[e][3]); }
; #pragma unroll
;     for (int o = 32; o > 0; o >>= 1) q += __shfl_xor(q, o);
;     const float rstd = rsqrtf(q * (1.f / 1024.f) + 1e-5f);
;     if (!writex && lane == 0) { f32x2 ms = {mu, rstd}; *(f32x2*)(p.lnstat + (size_t)row * 2) = ms; }
; #pragma unroll
;     for (int e = 0; e < 4; ++e) { const int col = e * 256 + lane * 4;
;       const f32x4 y = v[e] * rstd * *(const f32x4*)(g + col) + *(const f32x4*)(bta + col);
;       if (writex) *(f32x4*)(xr + col) = y;
;       if (sh) { const f32x4 hv = y * (*(const f32x4*)(sc + b * 6144 + col) + 1.f) + *(const f32x4*)(sh + b * 6144 + col); st4(p.H + (size_t)row * DM + col, hv[0], hv[1], hv[2], hv[3]); } }
.LBB0_779:
	s_or_b64 exec, exec, s[0:1]
	s_lshl_b32 s4, s79, 3
	v_mov_b32_e32 v1, v206
	s_mov_b32 s0, s4
	s_waitcnt lgkmcnt(0)
	s_barrier
	v_writelane_b32 v255, s0, 3
	v_ashrrev_i32_e32 v0, 6, v1
	v_add_u32_e32 v31, s4, v0
	v_writelane_b32 v255, s1, 4
	s_mov_b32 s0, 0x8000
	v_cmp_gt_i32_e32 vcc, s0, v31
	s_and_saveexec_b64 s[4:5], vcc
	s_cbranch_execz .LBB0_784
	v_cmp_lt_i32_e64 s[0:1], v209, v208
	v_and_b32_e32 v6, 63, v1
	v_readlane_b32 s8, v252, 60
	v_cndmask_b32_e64 v1, v207, v209, s[0:1]
	v_lshlrev_b32_e32 v32, 2, v1
	v_xor_b32_e32 v1, 16, v207
	v_cmp_lt_i32_e64 s[0:1], v1, v208
	v_readlane_b32 s9, v252, 61
	v_readlane_b32 s10, v252, 62
	v_cndmask_b32_e64 v1, v207, v1, s[0:1]
	v_lshlrev_b32_e32 v33, 2, v1
	v_xor_b32_e32 v1, 8, v207
	v_cmp_lt_i32_e64 s[0:1], v1, v208
	v_readlane_b32 s11, v252, 63
	v_readlane_b32 s12, v251, 0
	v_cndmask_b32_e64 v1, v207, v1, s[0:1]
	v_lshlrev_b32_e32 v34, 2, v1
	v_xor_b32_e32 v1, 4, v207
	v_cmp_lt_i32_e64 s[0:1], v1, v208
	v_readlane_b32 s13, v251, 1
	v_readlane_b32 s14, v251, 2
	v_cndmask_b32_e64 v1, v207, v1, s[0:1]
	v_lshlrev_b32_e32 v35, 2, v1
	v_xor_b32_e32 v1, 2, v207
	v_readlane_b32 s15, v251, 3
	v_readlane_b32 s16, v251, 4
	v_readlane_b32 s17, v251, 5
	v_cmp_lt_i32_e64 s[0:1], v1, v208
	v_readlane_b32 s18, v251, 6
	v_readlane_b32 s19, v251, 7
	v_readlane_b32 s20, v251, 8
	v_readlane_b32 s21, v251, 9
	v_readlane_b32 s22, v251, 10
	v_readlane_b32 s23, v251, 11
	s_mov_b64 s[8:9], s[16:17]
	v_cndmask_b32_e64 v1, v207, v1, s[0:1]
	v_lshlrev_b32_e32 v2, 4, v6
	v_mov_b32_e32 v3, 0
	s_mov_b64 s[10:11], s[18:19]
	s_mov_b64 s[12:13], s[20:21]
	s_mov_b64 s[14:15], s[22:23]
	v_lshlrev_b32_e32 v36, 2, v1
	v_xor_b32_e32 v1, 1, v207
	v_lshl_add_u64 v[16:17], s[12:13], 0, v[2:3]
	v_lshl_add_u64 v[18:19], s[14:15], 0, v[2:3]
	v_readlane_b32 s8, v252, 17
	v_cmp_lt_i32_e64 s[0:1], v1, v208
	v_readlane_b32 s16, v252, 25
	v_readlane_b32 s17, v252, 26
	v_cndmask_b32_e64 v1, v207, v1, s[0:1]
	s_mov_b64 s[0:1], 0x4000
	v_lshl_add_u64 v[4:5], s[16:17], 0, v[2:3]
	v_lshl_add_u64 v[20:21], v[4:5], 0, s[0:1]
	s_mov_b64 s[0:1], 0x3000
	v_readlane_b32 s9, v252, 18
	v_lshl_add_u64 v[22:23], v[4:5], 0, s[0:1]
	v_readlane_b32 s0, v255, 3
	v_lshlrev_b32_e32 v37, 2, v1
	v_readlane_b32 s10, v252, 19
	v_readlane_b32 s11, v252, 20
	v_readlane_b32 s12, v252, 21
	v_readlane_b32 s13, v252, 22
	v_readlane_b32 s14, v252, 23
	v_readlane_b32 s15, v252, 24
	v_readlane_b32 s18, v252, 27
	v_readlane_b32 s19, v252, 28
	v_readlane_b32 s20, v252, 29
	v_readlane_b32 s21, v252, 30
	v_readlane_b32 s22, v252, 31
	v_readlane_b32 s23, v252, 32
	v_ashrrev_i32_e32 v1, 31, v0
	s_mov_b32 s8, s0
	s_ashr_i32 s9, s0, 31
	v_lshl_add_u64 v[0:1], v[0:1], 0, s[8:9]
	v_readlane_b32 s8, v252, 0
	v_readlane_b32 s1, v255, 4
	v_readlane_b32 s9, v252, 1
	v_lshlrev_b64 v[4:5], 12, v[0:1]
	v_writelane_b32 v255, s0, 3
	v_lshl_add_u64 v[24:25], v[0:1], 3, s[8:9]
	v_or_b32_e32 v4, v4, v2
	v_lshlrev_b64 v[0:1], 11, v[0:1]
	s_lshl_b32 s6, s38, 3
	v_writelane_b32 v255, s1, 4
	v_readlane_b32 s14, v252, 6
	v_readlane_b32 s15, v252, 7
	v_lshl_add_u64 v[2:3], s[84:85], 0, v[4:5]
	s_mov_b64 s[0:1], 0x800
	v_lshl_or_b32 v0, v6, 3, v0
	v_readlane_b32 s10, v252, 2
	v_readlane_b32 s11, v252, 3
	v_readlane_b32 s12, v252, 4
	v_readlane_b32 s13, v252, 5
	s_ashr_i32 s7, s6, 31
	v_lshl_add_u64 v[26:27], v[2:3], 0, s[0:1]
	v_lshl_add_u64 v[0:1], s[14:15], 0, v[0:1]
	s_mov_b64 s[0:1], 0x400
	v_cmp_eq_u32_e32 vcc, 0, v6
	s_lshl_b64 s[8:9], s[6:7], 3
	s_lshl_b64 s[10:11], s[6:7], 12
	v_lshl_add_u64 v[28:29], v[0:1], 0, s[0:1]
	s_lshl_b64 s[12:13], s[6:7], 11
	s_mov_b64 s[14:15], 0
	v_mov_b32_e32 v38, 0x3727c5ac
	v_readlane_b32 s16, v252, 8
	v_readlane_b32 s17, v252, 9
	v_readlane_b32 s18, v252, 10
	v_readlane_b32 s19, v252, 11
	v_readlane_b32 s20, v252, 12
	v_readlane_b32 s21, v252, 13
	v_readlane_b32 s22, v252, 14
	v_readlane_b32 s23, v252, 15
	global_load_dwordx4 v[124:127], v[26:27], off offset:-2048
	global_load_dwordx4 v[128:131], v[26:27], off offset:-1024
	global_load_dwordx4 v[132:135], v[26:27], off
	global_load_dwordx4 v[136:139], v[26:27], off offset:1024
	s_waitcnt vmcnt(0)
	s_branch .LBB0_782
.LBB0_781:
	s_or_b64 exec, exec, s[0:1]
	s_movk_i32 s0, 0x7fff
	v_lshl_add_u64 v[24:25], v[24:25], 0, s[8:9]
	v_lshl_add_u64 v[26:27], v[26:27], 0, s[10:11]
	s_waitcnt vmcnt(5)
	v_pk_mul_f32 v[46:47], v[14:15], v[30:31] op_sel_hi:[1,0]
	v_pk_mul_f32 v[48:49], v[12:13], v[30:31] op_sel_hi:[1,0]
	v_pk_fma_f32 v[42:43], v[46:47], v[54:55], v[70:71]
	v_pk_fma_f32 v[40:41], v[48:49], v[52:53], v[68:69]
	v_pk_add_f32 v[48:49], v[86:87], 1.0 op_sel_hi:[1,0]
	v_pk_add_f32 v[50:51], v[84:85], 1.0 op_sel_hi:[1,0]
	v_pk_fma_f32 v[14:15], v[42:43], v[48:49], v[102:103]
	v_pk_fma_f32 v[12:13], v[40:41], v[50:51], v[100:101]
	s_nop 0
	v_cvt_pk_bf16_f32 v12, v12, v13
	v_cvt_pk_bf16_f32 v13, v14, v15
	global_store_dwordx2 v[28:29], v[12:13], off offset:-1024
	v_pk_mul_f32 v[46:47], v[10:11], v[30:31] op_sel_hi:[1,0]
	v_pk_mul_f32 v[48:49], v[8:9], v[30:31] op_sel_hi:[1,0]
	v_pk_fma_f32 v[42:43], v[46:47], v[58:59], v[74:75]
	v_pk_fma_f32 v[40:41], v[48:49], v[56:57], v[72:73]
	v_pk_add_f32 v[48:49], v[90:91], 1.0 op_sel_hi:[1,0]
	v_pk_add_f32 v[50:51], v[88:89], 1.0 op_sel_hi:[1,0]
	v_pk_fma_f32 v[10:11], v[42:43], v[48:49], v[106:107]
	v_pk_fma_f32 v[8:9], v[40:41], v[50:51], v[104:105]
	s_nop 0
	v_cvt_pk_bf16_f32 v8, v8, v9
	v_cvt_pk_bf16_f32 v9, v10, v11
	global_store_dwordx2 v[28:29], v[8:9], off offset:-512
	v_pk_mul_f32 v[46:47], v[6:7], v[30:31] op_sel_hi:[1,0]
	v_pk_mul_f32 v[48:49], v[4:5], v[30:31] op_sel_hi:[1,0]
	v_pk_fma_f32 v[42:43], v[46:47], v[62:63], v[78:79]
	v_pk_fma_f32 v[40:41], v[48:49], v[60:61], v[76:77]
	v_pk_add_f32 v[48:49], v[94:95], 1.0 op_sel_hi:[1,0]
	v_pk_add_f32 v[50:51], v[92:93], 1.0 op_sel_hi:[1,0]
	v_pk_fma_f32 v[6:7], v[42:43], v[48:49], v[110:111]
	v_pk_fma_f32 v[4:5], v[40:41], v[50:51], v[108:109]
	s_nop 0
	v_cvt_pk_bf16_f32 v4, v4, v5
	v_cvt_pk_bf16_f32 v5, v6, v7
	global_store_dwordx2 v[28:29], v[4:5], off
	v_pk_mul_f32 v[46:47], v[2:3], v[30:31] op_sel_hi:[1,0]
	v_pk_mul_f32 v[48:49], v[0:1], v[30:31] op_sel_hi:[1,0]
	v_pk_fma_f32 v[42:43], v[46:47], v[66:67], v[82:83]
	v_pk_fma_f32 v[40:41], v[48:49], v[64:65], v[80:81]
	v_pk_add_f32 v[48:49], v[98:99], 1.0 op_sel_hi:[1,0]
	v_pk_add_f32 v[50:51], v[96:97], 1.0 op_sel_hi:[1,0]
	v_pk_fma_f32 v[2:3], v[42:43], v[48:49], v[114:115]
	v_pk_fma_f32 v[0:1], v[40:41], v[50:51], v[112:113]
	s_nop 0
	v_cvt_pk_bf16_f32 v0, v0, v1
	v_cvt_pk_bf16_f32 v1, v2, v3
	global_store_dwordx2 v[28:29], v[0:1], off offset:512
	v_add_u32_e32 v31, s6, v31
	v_cmp_lt_i32_e64 s[0:1], s0, v31
	s_or_b64 s[14:15], s[0:1], s[14:15]
	v_lshl_add_u64 v[28:29], v[28:29], 0, s[12:13]
	s_andn2_b64 exec, exec, s[14:15]
	s_cbranch_execz .LBB0_784
; DI void phase_ln(const Params& p, const float* g, const float* bta, const float* sh, const float* sc, bool writex, int bid, int nb) {
;     ...
;     float* xr = p.out + (size_t)row * DM; const int b = row >> 12;
;     f32x4 v[4]; float s = 0.f;
; #pragma unroll
;     for (int e = 0; e < 4; ++e) { v[e] = *(const f32x4*)(xr + e * 256 + lane * 4); s += (v[e][0] + v[e][1]) + (v[e][2] + v[e][3]); }
; #pragma unroll
;     for (int o = 32; o > 0; o >>= 1) s += __shfl_xor(s, o);
;     const float mu = s * (1.f / 1024.f); float q = 0.f;
; #pragma unroll
;     for (int e = 0; e < 4; ++e) { v[e] -= mu; q += (v[e][0] * v[e][0] + v[e][1] * v[e][1]) + (v[e][2] * v[e][2] + v[e][3] * v[e][3]); }
; #pragma unroll
;     for (int o = 32; o > 0; o >>= 1) q += __shfl_xor(q, o);
;     const float rstd = rsqrtf(q * (1.f / 1024.f) + 1e-5f);
;     if (!writex && lane == 0) { f32x2 ms = {mu, rstd}; *(f32x2*)(p.lnstat + (size_t)row * 2) = ms; }
.LBB0_782:
	s_waitcnt vmcnt(5)
	v_mov_b64_e32 v[12:13], v[124:125]
	v_mov_b64_e32 v[14:15], v[126:127]
	v_mov_b64_e32 v[8:9], v[128:129]
	v_mov_b64_e32 v[10:11], v[130:131]
	v_mov_b64_e32 v[4:5], v[132:133]
	v_mov_b64_e32 v[6:7], v[134:135]
	v_mov_b64_e32 v[0:1], v[136:137]
	v_mov_b64_e32 v[2:3], v[138:139]
	v_ashrrev_i32_e32 v116, 12, v31
	v_mul_i32_i24_e32 v116, 0x1800, v116
	v_ashrrev_i32_e32 v117, 31, v116
	v_lshlrev_b64 v[116:117], 2, v[116:117]
	v_lshl_add_u64 v[118:119], v[20:21], 0, v[116:117]
	v_lshl_add_u64 v[116:117], v[22:23], 0, v[116:117]
	global_load_dwordx4 v[52:55], v[16:17], off
	global_load_dwordx4 v[68:71], v[18:19], off
	global_load_dwordx4 v[84:87], v[118:119], off
	global_load_dwordx4 v[100:103], v[116:117], off
	global_load_dwordx4 v[56:59], v[16:17], off offset:1024
	global_load_dwordx4 v[72:75], v[18:19], off offset:1024
	global_load_dwordx4 v[88:91], v[118:119], off offset:1024
	global_load_dwordx4 v[104:107], v[116:117], off offset:1024
	global_load_dwordx4 v[60:63], v[16:17], off offset:2048
	global_load_dwordx4 v[76:79], v[18:19], off offset:2048
	global_load_dwordx4 v[92:95], v[118:119], off offset:2048
	global_load_dwordx4 v[108:111], v[116:117], off offset:2048
	global_load_dwordx4 v[64:67], v[16:17], off offset:3072
	global_load_dwordx4 v[80:83], v[18:19], off offset:3072
	global_load_dwordx4 v[96:99], v[118:119], off offset:3072
	global_load_dwordx4 v[112:115], v[116:117], off offset:3072
	v_add_u32_e32 v140, s6, v31
	s_movk_i32 s100, 0x7fff
	v_cmp_ge_i32_e64 s[98:99], s100, v140
	v_lshl_add_u64 v[142:143], v[26:27], 0, s[10:11]
	s_nop 1
	v_cndmask_b32_e64 v142, v26, v142, s[98:99]
	v_cndmask_b32_e64 v143, v27, v143, s[98:99]
	global_load_dwordx4 v[124:127], v[142:143], off offset:-2048
	global_load_dwordx4 v[128:131], v[142:143], off offset:-1024
	global_load_dwordx4 v[132:135], v[142:143], off
	global_load_dwordx4 v[136:139], v[142:143], off offset:1024
	s_mov_b32 s0, 0x800000
	v_mov_b32_e32 v120, v13
	v_mov_b32_e32 v121, v14
	v_mov_b32_e32 v122, v12
	v_mov_b32_e32 v123, v15
	v_pk_add_f32 v[120:121], v[120:121], v[122:123]
	v_mov_b32_e32 v122, v8
	v_add_f32_e32 v120, v120, v121
	v_add_f32_e32 v40, 0, v120
	v_mov_b32_e32 v120, v9
	v_mov_b32_e32 v121, v10
	v_mov_b32_e32 v123, v11
	v_pk_add_f32 v[120:121], v[120:121], v[122:123]
	s_nop 0
	v_pk_add_f32 v[42:43], v[120:121], v[120:121] op_sel:[0,1] op_sel_hi:[1,0]
	v_add_f32_e32 v44, v4, v5
	v_add_f32_e32 v46, v6, v7
	v_mov_b32_e32 v41, v0
	v_mov_b32_e32 v43, v1
	v_mov_b32_e32 v45, v2
	v_mov_b32_e32 v47, v3
	v_pk_add_f32 v[40:41], v[40:41], v[42:43]
	v_pk_add_f32 v[42:43], v[44:45], v[46:47]
	s_nop 0
	v_pk_add_f32 v[40:41], v[40:41], v[42:43]
	s_nop 0
	v_add_f32_e32 v30, v40, v41
	ds_bpermute_b32 v39, v32, v30
	s_waitcnt lgkmcnt(0)
	v_add_f32_e32 v30, v30, v39
	ds_bpermute_b32 v39, v33, v30
	s_waitcnt lgkmcnt(0)
	v_add_f32_e32 v30, v30, v39
	ds_bpermute_b32 v39, v34, v30
	s_waitcnt lgkmcnt(0)
	v_add_f32_e32 v30, v30, v39
	ds_bpermute_b32 v39, v35, v30
	s_waitcnt lgkmcnt(0)
	v_add_f32_e32 v30, v30, v39
	ds_bpermute_b32 v39, v36, v30
	s_waitcnt lgkmcnt(0)
	v_add_f32_e32 v30, v30, v39
	ds_bpermute_b32 v39, v37, v30
	s_waitcnt lgkmcnt(0)
	v_add_f32_e32 v39, v30, v39
	v_fmamk_f32 v15, v39, 0xba800000, v15
	v_fmamk_f32 v14, v39, 0xba800000, v14
	v_fmamk_f32 v13, v39, 0xba800000, v13
	v_fmac_f32_e32 v12, 0xba800000, v39
	v_pk_mul_f32 v[40:41], v[14:15], v[14:15]
	v_pk_mul_f32 v[42:43], v[12:13], v[12:13]
	v_fmamk_f32 v11, v39, 0xba800000, v11
	v_pk_mov_b32 v[44:45], v[42:43], v[40:41] op_sel:[1,0]
	v_mov_b32_e32 v43, v41
	v_fmamk_f32 v10, v39, 0xba800000, v10
	v_fmamk_f32 v9, v39, 0xba800000, v9
	v_fmac_f32_e32 v8, 0xba800000, v39
	v_pk_add_f32 v[40:41], v[44:45], v[42:43]
	v_pk_mul_f32 v[42:43], v[10:11], v[10:11]
	v_pk_mul_f32 v[44:45], v[8:9], v[8:9]
	v_fmac_f32_e32 v4, 0xba800000, v39
	v_pk_mov_b32 v[46:47], v[44:45], v[42:43] op_sel:[1,0]
	v_mov_b32_e32 v45, v43
	v_fmamk_f32 v6, v39, 0xba800000, v6
	v_fmamk_f32 v5, v39, 0xba800000, v5
	v_mul_f32_e32 v30, v4, v4
	v_pk_add_f32 v[42:43], v[46:47], v[44:45]
	v_fmamk_f32 v7, v39, 0xba800000, v7
	v_pk_fma_f32 v[44:45], v[4:5], v[4:5], v[30:31] op_sel_hi:[1,1,0]
	v_mul_f32_e32 v30, v6, v6
	v_pk_add_f32 v[40:41], v[40:41], v[40:41] op_sel_hi:[0,1]
	v_pk_add_f32 v[42:43], v[42:43], v[42:43] op_sel_hi:[0,1]
	v_pk_fma_f32 v[46:47], v[6:7], v[6:7], v[30:31] op_sel_hi:[1,1,0]
	v_fmamk_f32 v3, v39, 0xba800000, v3
	v_fmamk_f32 v2, v39, 0xba800000, v2
	v_fmamk_f32 v1, v39, 0xba800000, v1
	v_fmac_f32_e32 v0, 0xba800000, v39
	v_mul_f32_e32 v44, v0, v0
	v_mul_f32_e32 v46, v1, v1
	v_mul_f32_e32 v40, v2, v2
	v_mul_f32_e32 v42, v3, v3
	v_pk_add_f32 v[44:45], v[44:45], v[46:47]
	v_pk_add_f32 v[40:41], v[40:41], v[42:43]
	s_nop 0
	v_pk_add_f32 v[40:41], v[44:45], v[40:41]
	s_nop 0
	v_add_f32_e32 v30, v40, v41
	ds_bpermute_b32 v40, v32, v30
	s_waitcnt lgkmcnt(0)
	v_add_f32_e32 v30, v30, v40
	ds_bpermute_b32 v40, v33, v30
	s_waitcnt lgkmcnt(0)
	v_add_f32_e32 v30, v30, v40
	ds_bpermute_b32 v40, v34, v30
	s_waitcnt lgkmcnt(0)
	v_add_f32_e32 v30, v30, v40
	ds_bpermute_b32 v40, v35, v30
	s_waitcnt lgkmcnt(0)
	v_add_f32_e32 v30, v30, v40
	ds_bpermute_b32 v40, v36, v30
	s_waitcnt lgkmcnt(0)
	v_add_f32_e32 v30, v30, v40
	ds_bpermute_b32 v40, v37, v30
	s_waitcnt lgkmcnt(0)
	v_add_f32_e32 v30, v30, v40
	v_fmamk_f32 v30, v30, 0x3a800000, v38
	v_cmp_gt_f32_e64 s[0:1], s0, v30
	v_mul_f32_e32 v40, 0x4b800000, v30
	s_nop 0
	v_cndmask_b32_e64 v30, v30, v40, s[0:1]
	v_rsq_f32_e32 v30, v30
	s_nop 0
	v_mul_f32_e32 v40, 0x45800000, v30
	v_cndmask_b32_e64 v30, v30, v40, s[0:1]
	s_and_saveexec_b64 s[0:1], vcc
	s_cbranch_execz .LBB0_781
	v_mul_f32_e32 v40, 0x3a800000, v39
	v_mov_b32_e32 v41, v30
	global_store_dwordx2 v[24:25], v[40:41], off
	s_branch .LBB0_781
